# mix part 2, layer 0: fourth-round fnet items moved to virtual blocks 32..55 (workgroups without a context attention item)
# baseline (speedup 1.0000x reference)
; DI void phase_mix(KP p, int l, char* lds) {
;     ...
;   for (int it = lb; it < e7; it += nlb) {
;     if (it >= e6) {
.Lperm_l0:
	s_add_i32 s46, s101, 32
	s_and_b32 s46, s46, 63
	s_addk_i32 s46, 0xc0
